# opt25 f32 matrix cores for the Hyena filter projection (v_mfma_f32_16x16x4_f32, f32 operands/accumulate) instead of per-lane VALU dot products through LDS; on v063
# speedup vs baseline: 1.0035x; 1.0035x over previous
.LBB0_116:
	s_add_i32 s10, s3, s91
	s_waitcnt lgkmcnt(0)
	s_barrier
	v_and_b32_e32 v36, 15, v130
	v_lshrrev_b32_e32 v37, 4, v130
	s_lshr_b32 s8, s3, 10
	s_lshl_b32 s8, s8, 11
	s_and_b32 s9, s3, 0x3ff
	s_add_i32 s8, s8, s9
	v_lshrrev_b32_e32 v92, 1, v36
	v_and_b32_e32 v93, 1, v36
	v_lshlrev_b32_e32 v93, 10, v93
	v_add3_u32 v93, v92, v93, s8
	v_lshl_add_u32 v93, v37, 14, v93
	v_lshlrev_b32_e32 v93, 2, v93
	v_add_u32_e32 v94, s9, v92
	v_cvt_f32_u32_e32 v94, v94
	v_fmamk_f32 v94, v94, 0x3b2ad55f, v31
	v_mul_f32_e32 v94, 0x40935d8e, v94
	v_xor_b32_e32 v38, 0x80000000, v94
	v_lshlrev_b32_e32 v95, 14, v92
	v_and_b32_e32 v96, 1, v36
	v_lshlrev_b32_e32 v96, 8, v96
	v_lshl_add_u32 v96, v37, 4, v96
	v_add_u32_e32 v39, v95, v96
	s_lshr_b32 s8, s91, 2
	s_lshl_b32 s8, s8, 9
	s_and_b32 s14, s91, 3
	s_lshl_b32 s14, s14, 6
	s_add_i32 s8, s8, s14
	s_addk_i32 s8, 0x4400
	v_add_u32_e32 v39, s8, v39
	s_lshl_b32 s9, s91, 4
	v_lshl_add_u32 v98, v37, 2, s9
	v_mov_b32_e32 v97, 0x3a001002
	s_mov_b32 s11, 0xc4ffe000
	s_mov_b64 s[14:15], s[56:57]
	global_load_dword v40, v93, s[14:15]
	s_add_u32 s14, s14, 0x4000
	s_addc_u32 s15, s15, 0
	global_load_dword v41, v93, s[14:15]
	s_add_u32 s14, s14, 0x4000
	s_addc_u32 s15, s15, 0
	global_load_dword v42, v93, s[14:15]
	s_add_u32 s14, s14, 0x4000
	s_addc_u32 s15, s15, 0
	global_load_dword v43, v93, s[14:15]
	s_add_u32 s14, s14, 0x34000
	s_addc_u32 s15, s15, 0
	global_load_dword v44, v93, s[14:15]
	s_add_u32 s14, s14, 0x4000
	s_addc_u32 s15, s15, 0
	global_load_dword v45, v93, s[14:15]
	s_add_u32 s14, s14, 0x4000
	s_addc_u32 s15, s15, 0
	global_load_dword v46, v93, s[14:15]
	s_add_u32 s14, s14, 0x4000
	s_addc_u32 s15, s15, 0
	global_load_dword v47, v93, s[14:15]
	s_add_u32 s14, s14, 0x34000
	s_addc_u32 s15, s15, 0
	global_load_dword v48, v93, s[14:15]
	s_add_u32 s14, s14, 0x4000
	s_addc_u32 s15, s15, 0
	global_load_dword v49, v93, s[14:15]
	s_add_u32 s14, s14, 0x4000
	s_addc_u32 s15, s15, 0
	global_load_dword v50, v93, s[14:15]
	s_add_u32 s14, s14, 0x4000
	s_addc_u32 s15, s15, 0
	global_load_dword v51, v93, s[14:15]
	s_add_u32 s14, s14, 0x34000
	s_addc_u32 s15, s15, 0
	global_load_dword v52, v93, s[14:15]
	s_add_u32 s14, s14, 0x4000
	s_addc_u32 s15, s15, 0
	global_load_dword v53, v93, s[14:15]
	s_add_u32 s14, s14, 0x4000
	s_addc_u32 s15, s15, 0
	global_load_dword v54, v93, s[14:15]
	s_add_u32 s14, s14, 0x4000
	s_addc_u32 s15, s15, 0
	global_load_dword v55, v93, s[14:15]
	v_lshlrev_b32_e32 v96, 8, v36
	v_lshl_add_u32 v96, v37, 4, v96
	s_lshl_b32 s14, s91, 12
	s_add_u32 s8, s70, 0x6400000
	s_addc_u32 s9, s71, 0
	s_add_u32 s8, s8, s14
	s_addc_u32 s9, s9, 0
	global_load_dwordx4 v[156:159], v96, s[8:9]
	global_load_dwordx4 v[160:163], v96, s[8:9] offset:64
	global_load_dwordx4 v[164:167], v96, s[8:9] offset:128
	global_load_dwordx4 v[168:171], v96, s[8:9] offset:192
	s_add_u32 s8, s8, 0x8000
	s_addc_u32 s9, s9, 0
	global_load_dwordx4 v[172:175], v96, s[8:9]
	global_load_dwordx4 v[176:179], v96, s[8:9] offset:64
	global_load_dwordx4 v[180:183], v96, s[8:9] offset:128
	global_load_dwordx4 v[184:187], v96, s[8:9] offset:192
	s_add_u32 s8, s8, 0x8000
	s_addc_u32 s9, s9, 0
	global_load_dwordx4 v[188:191], v96, s[8:9]
	global_load_dwordx4 v[192:195], v96, s[8:9] offset:64
	global_load_dwordx4 v[196:199], v96, s[8:9] offset:128
	global_load_dwordx4 v[200:203], v96, s[8:9] offset:192
	s_add_u32 s8, s8, 0x8000
	s_addc_u32 s9, s9, 0
	global_load_dwordx4 v[204:207], v96, s[8:9]
	global_load_dwordx4 v[208:211], v96, s[8:9] offset:64
	global_load_dwordx4 v[212:215], v96, s[8:9] offset:128
	global_load_dwordx4 v[216:219], v96, s[8:9] offset:192
	s_add_u32 s8, s8, 0x8000
	s_addc_u32 s9, s9, 0
	s_waitcnt vmcnt(12)
	v_mfma_f32_16x16x4_f32 v[88:91], v156, v40, 0
	v_mfma_f32_16x16x4_f32 v[88:91], v157, v41, v[88:91]
	v_mfma_f32_16x16x4_f32 v[88:91], v158, v42, v[88:91]
	v_mfma_f32_16x16x4_f32 v[88:91], v159, v43, v[88:91]
	v_mfma_f32_16x16x4_f32 v[88:91], v160, v44, v[88:91]
	v_mfma_f32_16x16x4_f32 v[88:91], v161, v45, v[88:91]
	v_mfma_f32_16x16x4_f32 v[88:91], v162, v46, v[88:91]
	v_mfma_f32_16x16x4_f32 v[88:91], v163, v47, v[88:91]
	v_mfma_f32_16x16x4_f32 v[88:91], v164, v48, v[88:91]
	v_mfma_f32_16x16x4_f32 v[88:91], v165, v49, v[88:91]
	v_mfma_f32_16x16x4_f32 v[88:91], v166, v50, v[88:91]
	v_mfma_f32_16x16x4_f32 v[88:91], v167, v51, v[88:91]
	v_mfma_f32_16x16x4_f32 v[88:91], v168, v52, v[88:91]
	v_mfma_f32_16x16x4_f32 v[88:91], v169, v53, v[88:91]
	v_mfma_f32_16x16x4_f32 v[88:91], v170, v54, v[88:91]
	v_mfma_f32_16x16x4_f32 v[88:91], v171, v55, v[88:91]
	v_mov_b32_e32 v99, v98
	v_add_u32_e32 v92, 0, v99
	v_cvt_f32_u32_e32 v92, v92
	v_add_u32_e32 v93, 1, v99
	v_cvt_f32_u32_e32 v93, v93
	v_add_u32_e32 v94, 2, v99
	v_cvt_f32_u32_e32 v94, v94
	v_add_u32_e32 v95, 3, v99
	v_cvt_f32_u32_e32 v95, v95
	v_mul_f32_e32 v0, v97, v92
	v_mul_f32_e32 v1, v97, v93
	v_mul_f32_e32 v2, v97, v94
	v_mul_f32_e32 v3, v97, v95
	v_fma_f32 v4, s11, v0, v92
	v_fma_f32 v5, s11, v1, v93
	v_fma_f32 v6, s11, v2, v94
	v_fma_f32 v7, s11, v3, v95
	v_fmac_f32_e32 v0, v4, v97
	v_fmac_f32_e32 v1, v5, v97
	v_fmac_f32_e32 v2, v6, v97
	v_fmac_f32_e32 v3, v7, v97
	v_mul_f32_e32 v0, v38, v0
	v_mul_f32_e32 v1, v38, v1
	v_mul_f32_e32 v2, v38, v2
	v_mul_f32_e32 v3, v38, v3
	v_mul_f32_e32 v0, 0x3fb8aa3b, v0
	v_mul_f32_e32 v1, 0x3fb8aa3b, v1
	v_mul_f32_e32 v2, 0x3fb8aa3b, v2
	v_mul_f32_e32 v3, 0x3fb8aa3b, v3
	v_exp_f32_e32 v0, v0
	v_exp_f32_e32 v1, v1
	v_exp_f32_e32 v2, v2
	v_exp_f32_e32 v3, v3
	s_nop 0
	v_mul_f32_e32 v88, v88, v0
	v_mul_f32_e32 v89, v89, v1
	v_mul_f32_e32 v90, v90, v2
	v_mul_f32_e32 v91, v91, v3
	ds_write_b128 v39, v[88:91]
	global_load_dwordx4 v[156:159], v96, s[8:9]
	global_load_dwordx4 v[160:163], v96, s[8:9] offset:64
	global_load_dwordx4 v[164:167], v96, s[8:9] offset:128
	global_load_dwordx4 v[168:171], v96, s[8:9] offset:192
	s_add_u32 s8, s8, 0x8000
	s_addc_u32 s9, s9, 0
	s_waitcnt vmcnt(12)
	v_mfma_f32_16x16x4_f32 v[88:91], v172, v40, 0
	v_mfma_f32_16x16x4_f32 v[88:91], v173, v41, v[88:91]
	v_mfma_f32_16x16x4_f32 v[88:91], v174, v42, v[88:91]
	v_mfma_f32_16x16x4_f32 v[88:91], v175, v43, v[88:91]
	v_mfma_f32_16x16x4_f32 v[88:91], v176, v44, v[88:91]
	v_mfma_f32_16x16x4_f32 v[88:91], v177, v45, v[88:91]
	v_mfma_f32_16x16x4_f32 v[88:91], v178, v46, v[88:91]
	v_mfma_f32_16x16x4_f32 v[88:91], v179, v47, v[88:91]
	v_mfma_f32_16x16x4_f32 v[88:91], v180, v48, v[88:91]
	v_mfma_f32_16x16x4_f32 v[88:91], v181, v49, v[88:91]
	v_mfma_f32_16x16x4_f32 v[88:91], v182, v50, v[88:91]
	v_mfma_f32_16x16x4_f32 v[88:91], v183, v51, v[88:91]
	v_mfma_f32_16x16x4_f32 v[88:91], v184, v52, v[88:91]
	v_mfma_f32_16x16x4_f32 v[88:91], v185, v53, v[88:91]
	v_mfma_f32_16x16x4_f32 v[88:91], v186, v54, v[88:91]
	v_mfma_f32_16x16x4_f32 v[88:91], v187, v55, v[88:91]
	v_add_u32_e32 v99, 0x80, v98
	v_add_u32_e32 v92, 0, v99
	v_cvt_f32_u32_e32 v92, v92
	v_add_u32_e32 v93, 1, v99
	v_cvt_f32_u32_e32 v93, v93
	v_add_u32_e32 v94, 2, v99
	v_cvt_f32_u32_e32 v94, v94
	v_add_u32_e32 v95, 3, v99
	v_cvt_f32_u32_e32 v95, v95
	v_mul_f32_e32 v0, v97, v92
	v_mul_f32_e32 v1, v97, v93
	v_mul_f32_e32 v2, v97, v94
	v_mul_f32_e32 v3, v97, v95
	v_fma_f32 v4, s11, v0, v92
	v_fma_f32 v5, s11, v1, v93
	v_fma_f32 v6, s11, v2, v94
	v_fma_f32 v7, s11, v3, v95
	v_fmac_f32_e32 v0, v4, v97
	v_fmac_f32_e32 v1, v5, v97
	v_fmac_f32_e32 v2, v6, v97
	v_fmac_f32_e32 v3, v7, v97
	v_mul_f32_e32 v0, v38, v0
	v_mul_f32_e32 v1, v38, v1
	v_mul_f32_e32 v2, v38, v2
	v_mul_f32_e32 v3, v38, v3
	v_mul_f32_e32 v0, 0x3fb8aa3b, v0
	v_mul_f32_e32 v1, 0x3fb8aa3b, v1
	v_mul_f32_e32 v2, 0x3fb8aa3b, v2
	v_mul_f32_e32 v3, 0x3fb8aa3b, v3
	v_exp_f32_e32 v0, v0
	v_exp_f32_e32 v1, v1
	v_exp_f32_e32 v2, v2
	v_exp_f32_e32 v3, v3
	s_nop 0
	v_mul_f32_e32 v88, v88, v0
	v_mul_f32_e32 v89, v89, v1
	v_mul_f32_e32 v90, v90, v2
	v_mul_f32_e32 v91, v91, v3
	ds_write_b128 v39, v[88:91] offset:1024
	global_load_dwordx4 v[172:175], v96, s[8:9]
	global_load_dwordx4 v[176:179], v96, s[8:9] offset:64
	global_load_dwordx4 v[180:183], v96, s[8:9] offset:128
	global_load_dwordx4 v[184:187], v96, s[8:9] offset:192
	s_add_u32 s8, s8, 0x8000
	s_addc_u32 s9, s9, 0
	s_waitcnt vmcnt(12)
	v_mfma_f32_16x16x4_f32 v[88:91], v188, v40, 0
	v_mfma_f32_16x16x4_f32 v[88:91], v189, v41, v[88:91]
	v_mfma_f32_16x16x4_f32 v[88:91], v190, v42, v[88:91]
	v_mfma_f32_16x16x4_f32 v[88:91], v191, v43, v[88:91]
	v_mfma_f32_16x16x4_f32 v[88:91], v192, v44, v[88:91]
	v_mfma_f32_16x16x4_f32 v[88:91], v193, v45, v[88:91]
	v_mfma_f32_16x16x4_f32 v[88:91], v194, v46, v[88:91]
	v_mfma_f32_16x16x4_f32 v[88:91], v195, v47, v[88:91]
	v_mfma_f32_16x16x4_f32 v[88:91], v196, v48, v[88:91]
	v_mfma_f32_16x16x4_f32 v[88:91], v197, v49, v[88:91]
	v_mfma_f32_16x16x4_f32 v[88:91], v198, v50, v[88:91]
	v_mfma_f32_16x16x4_f32 v[88:91], v199, v51, v[88:91]
	v_mfma_f32_16x16x4_f32 v[88:91], v200, v52, v[88:91]
	v_mfma_f32_16x16x4_f32 v[88:91], v201, v53, v[88:91]
	v_mfma_f32_16x16x4_f32 v[88:91], v202, v54, v[88:91]
	v_mfma_f32_16x16x4_f32 v[88:91], v203, v55, v[88:91]
	v_add_u32_e32 v99, 0x100, v98
	v_add_u32_e32 v92, 0, v99
	v_cvt_f32_u32_e32 v92, v92
	v_add_u32_e32 v93, 1, v99
	v_cvt_f32_u32_e32 v93, v93
	v_add_u32_e32 v94, 2, v99
	v_cvt_f32_u32_e32 v94, v94
	v_add_u32_e32 v95, 3, v99
	v_cvt_f32_u32_e32 v95, v95
	v_mul_f32_e32 v0, v97, v92
	v_mul_f32_e32 v1, v97, v93
	v_mul_f32_e32 v2, v97, v94
	v_mul_f32_e32 v3, v97, v95
	v_fma_f32 v4, s11, v0, v92
	v_fma_f32 v5, s11, v1, v93
	v_fma_f32 v6, s11, v2, v94
	v_fma_f32 v7, s11, v3, v95
	v_fmac_f32_e32 v0, v4, v97
	v_fmac_f32_e32 v1, v5, v97
	v_fmac_f32_e32 v2, v6, v97
	v_fmac_f32_e32 v3, v7, v97
	v_mul_f32_e32 v0, v38, v0
	v_mul_f32_e32 v1, v38, v1
	v_mul_f32_e32 v2, v38, v2
	v_mul_f32_e32 v3, v38, v3
	v_mul_f32_e32 v0, 0x3fb8aa3b, v0
	v_mul_f32_e32 v1, 0x3fb8aa3b, v1
	v_mul_f32_e32 v2, 0x3fb8aa3b, v2
	v_mul_f32_e32 v3, 0x3fb8aa3b, v3
	v_exp_f32_e32 v0, v0
	v_exp_f32_e32 v1, v1
	v_exp_f32_e32 v2, v2
	v_exp_f32_e32 v3, v3
	s_nop 0
	v_mul_f32_e32 v88, v88, v0
	v_mul_f32_e32 v89, v89, v1
	v_mul_f32_e32 v90, v90, v2
	v_mul_f32_e32 v91, v91, v3
	ds_write_b128 v39, v[88:91] offset:2048
	global_load_dwordx4 v[188:191], v96, s[8:9]
	global_load_dwordx4 v[192:195], v96, s[8:9] offset:64
	global_load_dwordx4 v[196:199], v96, s[8:9] offset:128
	global_load_dwordx4 v[200:203], v96, s[8:9] offset:192
	s_add_u32 s8, s8, 0x8000
	s_addc_u32 s9, s9, 0
	s_waitcnt vmcnt(12)
	v_mfma_f32_16x16x4_f32 v[88:91], v204, v40, 0
	v_mfma_f32_16x16x4_f32 v[88:91], v205, v41, v[88:91]
	v_mfma_f32_16x16x4_f32 v[88:91], v206, v42, v[88:91]
	v_mfma_f32_16x16x4_f32 v[88:91], v207, v43, v[88:91]
	v_mfma_f32_16x16x4_f32 v[88:91], v208, v44, v[88:91]
	v_mfma_f32_16x16x4_f32 v[88:91], v209, v45, v[88:91]
	v_mfma_f32_16x16x4_f32 v[88:91], v210, v46, v[88:91]
	v_mfma_f32_16x16x4_f32 v[88:91], v211, v47, v[88:91]
	v_mfma_f32_16x16x4_f32 v[88:91], v212, v48, v[88:91]
	v_mfma_f32_16x16x4_f32 v[88:91], v213, v49, v[88:91]
	v_mfma_f32_16x16x4_f32 v[88:91], v214, v50, v[88:91]
	v_mfma_f32_16x16x4_f32 v[88:91], v215, v51, v[88:91]
	v_mfma_f32_16x16x4_f32 v[88:91], v216, v52, v[88:91]
	v_mfma_f32_16x16x4_f32 v[88:91], v217, v53, v[88:91]
	v_mfma_f32_16x16x4_f32 v[88:91], v218, v54, v[88:91]
	v_mfma_f32_16x16x4_f32 v[88:91], v219, v55, v[88:91]
	v_add_u32_e32 v99, 0x180, v98
	v_add_u32_e32 v92, 0, v99
	v_cvt_f32_u32_e32 v92, v92
	v_add_u32_e32 v93, 1, v99
	v_cvt_f32_u32_e32 v93, v93
	v_add_u32_e32 v94, 2, v99
	v_cvt_f32_u32_e32 v94, v94
	v_add_u32_e32 v95, 3, v99
	v_cvt_f32_u32_e32 v95, v95
	v_mul_f32_e32 v0, v97, v92
	v_mul_f32_e32 v1, v97, v93
	v_mul_f32_e32 v2, v97, v94
	v_mul_f32_e32 v3, v97, v95
	v_fma_f32 v4, s11, v0, v92
	v_fma_f32 v5, s11, v1, v93
	v_fma_f32 v6, s11, v2, v94
	v_fma_f32 v7, s11, v3, v95
	v_fmac_f32_e32 v0, v4, v97
	v_fmac_f32_e32 v1, v5, v97
	v_fmac_f32_e32 v2, v6, v97
	v_fmac_f32_e32 v3, v7, v97
	v_mul_f32_e32 v0, v38, v0
	v_mul_f32_e32 v1, v38, v1
	v_mul_f32_e32 v2, v38, v2
	v_mul_f32_e32 v3, v38, v3
	v_mul_f32_e32 v0, 0x3fb8aa3b, v0
	v_mul_f32_e32 v1, 0x3fb8aa3b, v1
	v_mul_f32_e32 v2, 0x3fb8aa3b, v2
	v_mul_f32_e32 v3, 0x3fb8aa3b, v3
	v_exp_f32_e32 v0, v0
	v_exp_f32_e32 v1, v1
	v_exp_f32_e32 v2, v2
	v_exp_f32_e32 v3, v3
	s_nop 0
	v_mul_f32_e32 v88, v88, v0
	v_mul_f32_e32 v89, v89, v1
	v_mul_f32_e32 v90, v90, v2
	v_mul_f32_e32 v91, v91, v3
	ds_write_b128 v39, v[88:91] offset:3072
	global_load_dwordx4 v[204:207], v96, s[8:9]
	global_load_dwordx4 v[208:211], v96, s[8:9] offset:64
	global_load_dwordx4 v[212:215], v96, s[8:9] offset:128
	global_load_dwordx4 v[216:219], v96, s[8:9] offset:192
	s_add_u32 s8, s8, 0x8000
	s_addc_u32 s9, s9, 0
	s_waitcnt vmcnt(12)
	v_mfma_f32_16x16x4_f32 v[88:91], v156, v40, 0
	v_mfma_f32_16x16x4_f32 v[88:91], v157, v41, v[88:91]
	v_mfma_f32_16x16x4_f32 v[88:91], v158, v42, v[88:91]
	v_mfma_f32_16x16x4_f32 v[88:91], v159, v43, v[88:91]
	v_mfma_f32_16x16x4_f32 v[88:91], v160, v44, v[88:91]
	v_mfma_f32_16x16x4_f32 v[88:91], v161, v45, v[88:91]
	v_mfma_f32_16x16x4_f32 v[88:91], v162, v46, v[88:91]
	v_mfma_f32_16x16x4_f32 v[88:91], v163, v47, v[88:91]
	v_mfma_f32_16x16x4_f32 v[88:91], v164, v48, v[88:91]
	v_mfma_f32_16x16x4_f32 v[88:91], v165, v49, v[88:91]
	v_mfma_f32_16x16x4_f32 v[88:91], v166, v50, v[88:91]
	v_mfma_f32_16x16x4_f32 v[88:91], v167, v51, v[88:91]
	v_mfma_f32_16x16x4_f32 v[88:91], v168, v52, v[88:91]
	v_mfma_f32_16x16x4_f32 v[88:91], v169, v53, v[88:91]
	v_mfma_f32_16x16x4_f32 v[88:91], v170, v54, v[88:91]
	v_mfma_f32_16x16x4_f32 v[88:91], v171, v55, v[88:91]
	v_add_u32_e32 v99, 0x200, v98
	v_add_u32_e32 v92, 0, v99
	v_cvt_f32_u32_e32 v92, v92
	v_add_u32_e32 v93, 1, v99
	v_cvt_f32_u32_e32 v93, v93
	v_add_u32_e32 v94, 2, v99
	v_cvt_f32_u32_e32 v94, v94
	v_add_u32_e32 v95, 3, v99
	v_cvt_f32_u32_e32 v95, v95
	v_mul_f32_e32 v0, v97, v92
	v_mul_f32_e32 v1, v97, v93
	v_mul_f32_e32 v2, v97, v94
	v_mul_f32_e32 v3, v97, v95
	v_fma_f32 v4, s11, v0, v92
	v_fma_f32 v5, s11, v1, v93
	v_fma_f32 v6, s11, v2, v94
	v_fma_f32 v7, s11, v3, v95
	v_fmac_f32_e32 v0, v4, v97
	v_fmac_f32_e32 v1, v5, v97
	v_fmac_f32_e32 v2, v6, v97
	v_fmac_f32_e32 v3, v7, v97
	v_mul_f32_e32 v0, v38, v0
	v_mul_f32_e32 v1, v38, v1
	v_mul_f32_e32 v2, v38, v2
	v_mul_f32_e32 v3, v38, v3
	v_mul_f32_e32 v0, 0x3fb8aa3b, v0
	v_mul_f32_e32 v1, 0x3fb8aa3b, v1
	v_mul_f32_e32 v2, 0x3fb8aa3b, v2
	v_mul_f32_e32 v3, 0x3fb8aa3b, v3
	v_exp_f32_e32 v0, v0
	v_exp_f32_e32 v1, v1
	v_exp_f32_e32 v2, v2
	v_exp_f32_e32 v3, v3
	s_nop 0
	v_mul_f32_e32 v88, v88, v0
	v_mul_f32_e32 v89, v89, v1
	v_mul_f32_e32 v90, v90, v2
	v_mul_f32_e32 v91, v91, v3
	ds_write_b128 v39, v[88:91] offset:4096
	global_load_dwordx4 v[156:159], v96, s[8:9]
	global_load_dwordx4 v[160:163], v96, s[8:9] offset:64
	global_load_dwordx4 v[164:167], v96, s[8:9] offset:128
	global_load_dwordx4 v[168:171], v96, s[8:9] offset:192
	s_add_u32 s8, s8, 0x8000
	s_addc_u32 s9, s9, 0
	s_waitcnt vmcnt(12)
	v_mfma_f32_16x16x4_f32 v[88:91], v172, v40, 0
	v_mfma_f32_16x16x4_f32 v[88:91], v173, v41, v[88:91]
	v_mfma_f32_16x16x4_f32 v[88:91], v174, v42, v[88:91]
	v_mfma_f32_16x16x4_f32 v[88:91], v175, v43, v[88:91]
	v_mfma_f32_16x16x4_f32 v[88:91], v176, v44, v[88:91]
	v_mfma_f32_16x16x4_f32 v[88:91], v177, v45, v[88:91]
	v_mfma_f32_16x16x4_f32 v[88:91], v178, v46, v[88:91]
	v_mfma_f32_16x16x4_f32 v[88:91], v179, v47, v[88:91]
	v_mfma_f32_16x16x4_f32 v[88:91], v180, v48, v[88:91]
	v_mfma_f32_16x16x4_f32 v[88:91], v181, v49, v[88:91]
	v_mfma_f32_16x16x4_f32 v[88:91], v182, v50, v[88:91]
	v_mfma_f32_16x16x4_f32 v[88:91], v183, v51, v[88:91]
	v_mfma_f32_16x16x4_f32 v[88:91], v184, v52, v[88:91]
	v_mfma_f32_16x16x4_f32 v[88:91], v185, v53, v[88:91]
	v_mfma_f32_16x16x4_f32 v[88:91], v186, v54, v[88:91]
	v_mfma_f32_16x16x4_f32 v[88:91], v187, v55, v[88:91]
	v_add_u32_e32 v99, 0x280, v98
	v_add_u32_e32 v92, 0, v99
	v_cvt_f32_u32_e32 v92, v92
	v_add_u32_e32 v93, 1, v99
	v_cvt_f32_u32_e32 v93, v93
	v_add_u32_e32 v94, 2, v99
	v_cvt_f32_u32_e32 v94, v94
	v_add_u32_e32 v95, 3, v99
	v_cvt_f32_u32_e32 v95, v95
	v_mul_f32_e32 v0, v97, v92
	v_mul_f32_e32 v1, v97, v93
	v_mul_f32_e32 v2, v97, v94
	v_mul_f32_e32 v3, v97, v95
	v_fma_f32 v4, s11, v0, v92
	v_fma_f32 v5, s11, v1, v93
	v_fma_f32 v6, s11, v2, v94
	v_fma_f32 v7, s11, v3, v95
	v_fmac_f32_e32 v0, v4, v97
	v_fmac_f32_e32 v1, v5, v97
	v_fmac_f32_e32 v2, v6, v97
	v_fmac_f32_e32 v3, v7, v97
	v_mul_f32_e32 v0, v38, v0
	v_mul_f32_e32 v1, v38, v1
	v_mul_f32_e32 v2, v38, v2
	v_mul_f32_e32 v3, v38, v3
	v_mul_f32_e32 v0, 0x3fb8aa3b, v0
	v_mul_f32_e32 v1, 0x3fb8aa3b, v1
	v_mul_f32_e32 v2, 0x3fb8aa3b, v2
	v_mul_f32_e32 v3, 0x3fb8aa3b, v3
	v_exp_f32_e32 v0, v0
	v_exp_f32_e32 v1, v1
	v_exp_f32_e32 v2, v2
	v_exp_f32_e32 v3, v3
	s_nop 0
	v_mul_f32_e32 v88, v88, v0
	v_mul_f32_e32 v89, v89, v1
	v_mul_f32_e32 v90, v90, v2
	v_mul_f32_e32 v91, v91, v3
	ds_write_b128 v39, v[88:91] offset:5120
	global_load_dwordx4 v[172:175], v96, s[8:9]
	global_load_dwordx4 v[176:179], v96, s[8:9] offset:64
	global_load_dwordx4 v[180:183], v96, s[8:9] offset:128
	global_load_dwordx4 v[184:187], v96, s[8:9] offset:192
	s_add_u32 s8, s8, 0x8000
	s_addc_u32 s9, s9, 0
	s_waitcnt vmcnt(12)
	v_mfma_f32_16x16x4_f32 v[88:91], v188, v40, 0
	v_mfma_f32_16x16x4_f32 v[88:91], v189, v41, v[88:91]
	v_mfma_f32_16x16x4_f32 v[88:91], v190, v42, v[88:91]
	v_mfma_f32_16x16x4_f32 v[88:91], v191, v43, v[88:91]
	v_mfma_f32_16x16x4_f32 v[88:91], v192, v44, v[88:91]
	v_mfma_f32_16x16x4_f32 v[88:91], v193, v45, v[88:91]
	v_mfma_f32_16x16x4_f32 v[88:91], v194, v46, v[88:91]
	v_mfma_f32_16x16x4_f32 v[88:91], v195, v47, v[88:91]
	v_mfma_f32_16x16x4_f32 v[88:91], v196, v48, v[88:91]
	v_mfma_f32_16x16x4_f32 v[88:91], v197, v49, v[88:91]
	v_mfma_f32_16x16x4_f32 v[88:91], v198, v50, v[88:91]
	v_mfma_f32_16x16x4_f32 v[88:91], v199, v51, v[88:91]
	v_mfma_f32_16x16x4_f32 v[88:91], v200, v52, v[88:91]
	v_mfma_f32_16x16x4_f32 v[88:91], v201, v53, v[88:91]
	v_mfma_f32_16x16x4_f32 v[88:91], v202, v54, v[88:91]
	v_mfma_f32_16x16x4_f32 v[88:91], v203, v55, v[88:91]
	v_add_u32_e32 v99, 0x300, v98
	v_add_u32_e32 v92, 0, v99
	v_cvt_f32_u32_e32 v92, v92
	v_add_u32_e32 v93, 1, v99
	v_cvt_f32_u32_e32 v93, v93
	v_add_u32_e32 v94, 2, v99
	v_cvt_f32_u32_e32 v94, v94
	v_add_u32_e32 v95, 3, v99
	v_cvt_f32_u32_e32 v95, v95
	v_mul_f32_e32 v0, v97, v92
	v_mul_f32_e32 v1, v97, v93
	v_mul_f32_e32 v2, v97, v94
	v_mul_f32_e32 v3, v97, v95
	v_fma_f32 v4, s11, v0, v92
	v_fma_f32 v5, s11, v1, v93
	v_fma_f32 v6, s11, v2, v94
	v_fma_f32 v7, s11, v3, v95
	v_fmac_f32_e32 v0, v4, v97
	v_fmac_f32_e32 v1, v5, v97
	v_fmac_f32_e32 v2, v6, v97
	v_fmac_f32_e32 v3, v7, v97
	v_mul_f32_e32 v0, v38, v0
	v_mul_f32_e32 v1, v38, v1
	v_mul_f32_e32 v2, v38, v2
	v_mul_f32_e32 v3, v38, v3
	v_mul_f32_e32 v0, 0x3fb8aa3b, v0
	v_mul_f32_e32 v1, 0x3fb8aa3b, v1
	v_mul_f32_e32 v2, 0x3fb8aa3b, v2
	v_mul_f32_e32 v3, 0x3fb8aa3b, v3
	v_exp_f32_e32 v0, v0
	v_exp_f32_e32 v1, v1
	v_exp_f32_e32 v2, v2
	v_exp_f32_e32 v3, v3
	s_nop 0
	v_mul_f32_e32 v88, v88, v0
	v_mul_f32_e32 v89, v89, v1
	v_mul_f32_e32 v90, v90, v2
	v_mul_f32_e32 v91, v91, v3
	ds_write_b128 v39, v[88:91] offset:6144
	global_load_dwordx4 v[188:191], v96, s[8:9]
	global_load_dwordx4 v[192:195], v96, s[8:9] offset:64
	global_load_dwordx4 v[196:199], v96, s[8:9] offset:128
	global_load_dwordx4 v[200:203], v96, s[8:9] offset:192
	s_add_u32 s8, s8, 0x8000
	s_addc_u32 s9, s9, 0
	s_waitcnt vmcnt(12)
	v_mfma_f32_16x16x4_f32 v[88:91], v204, v40, 0
	v_mfma_f32_16x16x4_f32 v[88:91], v205, v41, v[88:91]
	v_mfma_f32_16x16x4_f32 v[88:91], v206, v42, v[88:91]
	v_mfma_f32_16x16x4_f32 v[88:91], v207, v43, v[88:91]
	v_mfma_f32_16x16x4_f32 v[88:91], v208, v44, v[88:91]
	v_mfma_f32_16x16x4_f32 v[88:91], v209, v45, v[88:91]
	v_mfma_f32_16x16x4_f32 v[88:91], v210, v46, v[88:91]
	v_mfma_f32_16x16x4_f32 v[88:91], v211, v47, v[88:91]
	v_mfma_f32_16x16x4_f32 v[88:91], v212, v48, v[88:91]
	v_mfma_f32_16x16x4_f32 v[88:91], v213, v49, v[88:91]
	v_mfma_f32_16x16x4_f32 v[88:91], v214, v50, v[88:91]
	v_mfma_f32_16x16x4_f32 v[88:91], v215, v51, v[88:91]
	v_mfma_f32_16x16x4_f32 v[88:91], v216, v52, v[88:91]
	v_mfma_f32_16x16x4_f32 v[88:91], v217, v53, v[88:91]
	v_mfma_f32_16x16x4_f32 v[88:91], v218, v54, v[88:91]
	v_mfma_f32_16x16x4_f32 v[88:91], v219, v55, v[88:91]
	v_add_u32_e32 v99, 0x380, v98
	v_add_u32_e32 v92, 0, v99
	v_cvt_f32_u32_e32 v92, v92
	v_add_u32_e32 v93, 1, v99
	v_cvt_f32_u32_e32 v93, v93
	v_add_u32_e32 v94, 2, v99
	v_cvt_f32_u32_e32 v94, v94
	v_add_u32_e32 v95, 3, v99
	v_cvt_f32_u32_e32 v95, v95
	v_mul_f32_e32 v0, v97, v92
	v_mul_f32_e32 v1, v97, v93
	v_mul_f32_e32 v2, v97, v94
	v_mul_f32_e32 v3, v97, v95
	v_fma_f32 v4, s11, v0, v92
	v_fma_f32 v5, s11, v1, v93
	v_fma_f32 v6, s11, v2, v94
	v_fma_f32 v7, s11, v3, v95
	v_fmac_f32_e32 v0, v4, v97
	v_fmac_f32_e32 v1, v5, v97
	v_fmac_f32_e32 v2, v6, v97
	v_fmac_f32_e32 v3, v7, v97
	v_mul_f32_e32 v0, v38, v0
	v_mul_f32_e32 v1, v38, v1
	v_mul_f32_e32 v2, v38, v2
	v_mul_f32_e32 v3, v38, v3
	v_mul_f32_e32 v0, 0x3fb8aa3b, v0
	v_mul_f32_e32 v1, 0x3fb8aa3b, v1
	v_mul_f32_e32 v2, 0x3fb8aa3b, v2
	v_mul_f32_e32 v3, 0x3fb8aa3b, v3
	v_exp_f32_e32 v0, v0
	v_exp_f32_e32 v1, v1
	v_exp_f32_e32 v2, v2
	v_exp_f32_e32 v3, v3
	s_nop 0
	v_mul_f32_e32 v88, v88, v0
	v_mul_f32_e32 v89, v89, v1
	v_mul_f32_e32 v90, v90, v2
	v_mul_f32_e32 v91, v91, v3
	ds_write_b128 v39, v[88:91] offset:7168
	global_load_dwordx4 v[204:207], v96, s[8:9]
	global_load_dwordx4 v[208:211], v96, s[8:9] offset:64
	global_load_dwordx4 v[212:215], v96, s[8:9] offset:128
	global_load_dwordx4 v[216:219], v96, s[8:9] offset:192
	s_add_u32 s8, s8, 0x8000
	s_addc_u32 s9, s9, 0
	s_waitcnt vmcnt(12)
	v_mfma_f32_16x16x4_f32 v[88:91], v156, v40, 0
	v_mfma_f32_16x16x4_f32 v[88:91], v157, v41, v[88:91]
	v_mfma_f32_16x16x4_f32 v[88:91], v158, v42, v[88:91]
	v_mfma_f32_16x16x4_f32 v[88:91], v159, v43, v[88:91]
	v_mfma_f32_16x16x4_f32 v[88:91], v160, v44, v[88:91]
	v_mfma_f32_16x16x4_f32 v[88:91], v161, v45, v[88:91]
	v_mfma_f32_16x16x4_f32 v[88:91], v162, v46, v[88:91]
	v_mfma_f32_16x16x4_f32 v[88:91], v163, v47, v[88:91]
	v_mfma_f32_16x16x4_f32 v[88:91], v164, v48, v[88:91]
	v_mfma_f32_16x16x4_f32 v[88:91], v165, v49, v[88:91]
	v_mfma_f32_16x16x4_f32 v[88:91], v166, v50, v[88:91]
	v_mfma_f32_16x16x4_f32 v[88:91], v167, v51, v[88:91]
	v_mfma_f32_16x16x4_f32 v[88:91], v168, v52, v[88:91]
	v_mfma_f32_16x16x4_f32 v[88:91], v169, v53, v[88:91]
	v_mfma_f32_16x16x4_f32 v[88:91], v170, v54, v[88:91]
	v_mfma_f32_16x16x4_f32 v[88:91], v171, v55, v[88:91]
	v_add_u32_e32 v99, 0x400, v98
	v_add_u32_e32 v92, 0, v99
	v_cvt_f32_u32_e32 v92, v92
	v_add_u32_e32 v93, 1, v99
	v_cvt_f32_u32_e32 v93, v93
	v_add_u32_e32 v94, 2, v99
	v_cvt_f32_u32_e32 v94, v94
	v_add_u32_e32 v95, 3, v99
	v_cvt_f32_u32_e32 v95, v95
	v_mul_f32_e32 v0, v97, v92
	v_mul_f32_e32 v1, v97, v93
	v_mul_f32_e32 v2, v97, v94
	v_mul_f32_e32 v3, v97, v95
	v_fma_f32 v4, s11, v0, v92
	v_fma_f32 v5, s11, v1, v93
	v_fma_f32 v6, s11, v2, v94
	v_fma_f32 v7, s11, v3, v95
	v_fmac_f32_e32 v0, v4, v97
	v_fmac_f32_e32 v1, v5, v97
	v_fmac_f32_e32 v2, v6, v97
	v_fmac_f32_e32 v3, v7, v97
	v_mul_f32_e32 v0, v38, v0
	v_mul_f32_e32 v1, v38, v1
	v_mul_f32_e32 v2, v38, v2
	v_mul_f32_e32 v3, v38, v3
	v_mul_f32_e32 v0, 0x3fb8aa3b, v0
	v_mul_f32_e32 v1, 0x3fb8aa3b, v1
	v_mul_f32_e32 v2, 0x3fb8aa3b, v2
	v_mul_f32_e32 v3, 0x3fb8aa3b, v3
	v_exp_f32_e32 v0, v0
	v_exp_f32_e32 v1, v1
	v_exp_f32_e32 v2, v2
	v_exp_f32_e32 v3, v3
	s_nop 0
	v_mul_f32_e32 v88, v88, v0
	v_mul_f32_e32 v89, v89, v1
	v_mul_f32_e32 v90, v90, v2
	v_mul_f32_e32 v91, v91, v3
	ds_write_b128 v39, v[88:91] offset:8192
	global_load_dwordx4 v[156:159], v96, s[8:9]
	global_load_dwordx4 v[160:163], v96, s[8:9] offset:64
	global_load_dwordx4 v[164:167], v96, s[8:9] offset:128
	global_load_dwordx4 v[168:171], v96, s[8:9] offset:192
	s_add_u32 s8, s8, 0x8000
	s_addc_u32 s9, s9, 0
	s_waitcnt vmcnt(12)
	v_mfma_f32_16x16x4_f32 v[88:91], v172, v40, 0
	v_mfma_f32_16x16x4_f32 v[88:91], v173, v41, v[88:91]
	v_mfma_f32_16x16x4_f32 v[88:91], v174, v42, v[88:91]
	v_mfma_f32_16x16x4_f32 v[88:91], v175, v43, v[88:91]
	v_mfma_f32_16x16x4_f32 v[88:91], v176, v44, v[88:91]
	v_mfma_f32_16x16x4_f32 v[88:91], v177, v45, v[88:91]
	v_mfma_f32_16x16x4_f32 v[88:91], v178, v46, v[88:91]
	v_mfma_f32_16x16x4_f32 v[88:91], v179, v47, v[88:91]
	v_mfma_f32_16x16x4_f32 v[88:91], v180, v48, v[88:91]
	v_mfma_f32_16x16x4_f32 v[88:91], v181, v49, v[88:91]
	v_mfma_f32_16x16x4_f32 v[88:91], v182, v50, v[88:91]
	v_mfma_f32_16x16x4_f32 v[88:91], v183, v51, v[88:91]
	v_mfma_f32_16x16x4_f32 v[88:91], v184, v52, v[88:91]
	v_mfma_f32_16x16x4_f32 v[88:91], v185, v53, v[88:91]
	v_mfma_f32_16x16x4_f32 v[88:91], v186, v54, v[88:91]
	v_mfma_f32_16x16x4_f32 v[88:91], v187, v55, v[88:91]
	v_add_u32_e32 v99, 0x480, v98
	v_add_u32_e32 v92, 0, v99
	v_cvt_f32_u32_e32 v92, v92
	v_add_u32_e32 v93, 1, v99
	v_cvt_f32_u32_e32 v93, v93
	v_add_u32_e32 v94, 2, v99
	v_cvt_f32_u32_e32 v94, v94
	v_add_u32_e32 v95, 3, v99
	v_cvt_f32_u32_e32 v95, v95
	v_mul_f32_e32 v0, v97, v92
	v_mul_f32_e32 v1, v97, v93
	v_mul_f32_e32 v2, v97, v94
	v_mul_f32_e32 v3, v97, v95
	v_fma_f32 v4, s11, v0, v92
	v_fma_f32 v5, s11, v1, v93
	v_fma_f32 v6, s11, v2, v94
	v_fma_f32 v7, s11, v3, v95
	v_fmac_f32_e32 v0, v4, v97
	v_fmac_f32_e32 v1, v5, v97
	v_fmac_f32_e32 v2, v6, v97
	v_fmac_f32_e32 v3, v7, v97
	v_mul_f32_e32 v0, v38, v0
	v_mul_f32_e32 v1, v38, v1
	v_mul_f32_e32 v2, v38, v2
	v_mul_f32_e32 v3, v38, v3
	v_mul_f32_e32 v0, 0x3fb8aa3b, v0
	v_mul_f32_e32 v1, 0x3fb8aa3b, v1
	v_mul_f32_e32 v2, 0x3fb8aa3b, v2
	v_mul_f32_e32 v3, 0x3fb8aa3b, v3
	v_exp_f32_e32 v0, v0
	v_exp_f32_e32 v1, v1
	v_exp_f32_e32 v2, v2
	v_exp_f32_e32 v3, v3
	s_nop 0
	v_mul_f32_e32 v88, v88, v0
	v_mul_f32_e32 v89, v89, v1
	v_mul_f32_e32 v90, v90, v2
	v_mul_f32_e32 v91, v91, v3
	ds_write_b128 v39, v[88:91] offset:9216
	global_load_dwordx4 v[172:175], v96, s[8:9]
	global_load_dwordx4 v[176:179], v96, s[8:9] offset:64
	global_load_dwordx4 v[180:183], v96, s[8:9] offset:128
	global_load_dwordx4 v[184:187], v96, s[8:9] offset:192
	s_add_u32 s8, s8, 0x8000
	s_addc_u32 s9, s9, 0
	s_waitcnt vmcnt(12)
	v_mfma_f32_16x16x4_f32 v[88:91], v188, v40, 0
	v_mfma_f32_16x16x4_f32 v[88:91], v189, v41, v[88:91]
	v_mfma_f32_16x16x4_f32 v[88:91], v190, v42, v[88:91]
	v_mfma_f32_16x16x4_f32 v[88:91], v191, v43, v[88:91]
	v_mfma_f32_16x16x4_f32 v[88:91], v192, v44, v[88:91]
	v_mfma_f32_16x16x4_f32 v[88:91], v193, v45, v[88:91]
	v_mfma_f32_16x16x4_f32 v[88:91], v194, v46, v[88:91]
	v_mfma_f32_16x16x4_f32 v[88:91], v195, v47, v[88:91]
	v_mfma_f32_16x16x4_f32 v[88:91], v196, v48, v[88:91]
	v_mfma_f32_16x16x4_f32 v[88:91], v197, v49, v[88:91]
	v_mfma_f32_16x16x4_f32 v[88:91], v198, v50, v[88:91]
	v_mfma_f32_16x16x4_f32 v[88:91], v199, v51, v[88:91]
	v_mfma_f32_16x16x4_f32 v[88:91], v200, v52, v[88:91]
	v_mfma_f32_16x16x4_f32 v[88:91], v201, v53, v[88:91]
	v_mfma_f32_16x16x4_f32 v[88:91], v202, v54, v[88:91]
	v_mfma_f32_16x16x4_f32 v[88:91], v203, v55, v[88:91]
	v_add_u32_e32 v99, 0x500, v98
	v_add_u32_e32 v92, 0, v99
	v_cvt_f32_u32_e32 v92, v92
	v_add_u32_e32 v93, 1, v99
	v_cvt_f32_u32_e32 v93, v93
	v_add_u32_e32 v94, 2, v99
	v_cvt_f32_u32_e32 v94, v94
	v_add_u32_e32 v95, 3, v99
	v_cvt_f32_u32_e32 v95, v95
	v_mul_f32_e32 v0, v97, v92
	v_mul_f32_e32 v1, v97, v93
	v_mul_f32_e32 v2, v97, v94
	v_mul_f32_e32 v3, v97, v95
	v_fma_f32 v4, s11, v0, v92
	v_fma_f32 v5, s11, v1, v93
	v_fma_f32 v6, s11, v2, v94
	v_fma_f32 v7, s11, v3, v95
	v_fmac_f32_e32 v0, v4, v97
	v_fmac_f32_e32 v1, v5, v97
	v_fmac_f32_e32 v2, v6, v97
	v_fmac_f32_e32 v3, v7, v97
	v_mul_f32_e32 v0, v38, v0
	v_mul_f32_e32 v1, v38, v1
	v_mul_f32_e32 v2, v38, v2
	v_mul_f32_e32 v3, v38, v3
	v_mul_f32_e32 v0, 0x3fb8aa3b, v0
	v_mul_f32_e32 v1, 0x3fb8aa3b, v1
	v_mul_f32_e32 v2, 0x3fb8aa3b, v2
	v_mul_f32_e32 v3, 0x3fb8aa3b, v3
	v_exp_f32_e32 v0, v0
	v_exp_f32_e32 v1, v1
	v_exp_f32_e32 v2, v2
	v_exp_f32_e32 v3, v3
	s_nop 0
	v_mul_f32_e32 v88, v88, v0
	v_mul_f32_e32 v89, v89, v1
	v_mul_f32_e32 v90, v90, v2
	v_mul_f32_e32 v91, v91, v3
	ds_write_b128 v39, v[88:91] offset:10240
	global_load_dwordx4 v[188:191], v96, s[8:9]
	global_load_dwordx4 v[192:195], v96, s[8:9] offset:64
	global_load_dwordx4 v[196:199], v96, s[8:9] offset:128
	global_load_dwordx4 v[200:203], v96, s[8:9] offset:192
	s_add_u32 s8, s8, 0x8000
	s_addc_u32 s9, s9, 0
	s_waitcnt vmcnt(12)
	v_mfma_f32_16x16x4_f32 v[88:91], v204, v40, 0
	v_mfma_f32_16x16x4_f32 v[88:91], v205, v41, v[88:91]
	v_mfma_f32_16x16x4_f32 v[88:91], v206, v42, v[88:91]
	v_mfma_f32_16x16x4_f32 v[88:91], v207, v43, v[88:91]
	v_mfma_f32_16x16x4_f32 v[88:91], v208, v44, v[88:91]
	v_mfma_f32_16x16x4_f32 v[88:91], v209, v45, v[88:91]
	v_mfma_f32_16x16x4_f32 v[88:91], v210, v46, v[88:91]
	v_mfma_f32_16x16x4_f32 v[88:91], v211, v47, v[88:91]
	v_mfma_f32_16x16x4_f32 v[88:91], v212, v48, v[88:91]
	v_mfma_f32_16x16x4_f32 v[88:91], v213, v49, v[88:91]
	v_mfma_f32_16x16x4_f32 v[88:91], v214, v50, v[88:91]
	v_mfma_f32_16x16x4_f32 v[88:91], v215, v51, v[88:91]
	v_mfma_f32_16x16x4_f32 v[88:91], v216, v52, v[88:91]
	v_mfma_f32_16x16x4_f32 v[88:91], v217, v53, v[88:91]
	v_mfma_f32_16x16x4_f32 v[88:91], v218, v54, v[88:91]
	v_mfma_f32_16x16x4_f32 v[88:91], v219, v55, v[88:91]
	v_add_u32_e32 v99, 0x580, v98
	v_add_u32_e32 v92, 0, v99
	v_cvt_f32_u32_e32 v92, v92
	v_add_u32_e32 v93, 1, v99
	v_cvt_f32_u32_e32 v93, v93
	v_add_u32_e32 v94, 2, v99
	v_cvt_f32_u32_e32 v94, v94
	v_add_u32_e32 v95, 3, v99
	v_cvt_f32_u32_e32 v95, v95
	v_mul_f32_e32 v0, v97, v92
	v_mul_f32_e32 v1, v97, v93
	v_mul_f32_e32 v2, v97, v94
	v_mul_f32_e32 v3, v97, v95
	v_fma_f32 v4, s11, v0, v92
	v_fma_f32 v5, s11, v1, v93
	v_fma_f32 v6, s11, v2, v94
	v_fma_f32 v7, s11, v3, v95
	v_fmac_f32_e32 v0, v4, v97
	v_fmac_f32_e32 v1, v5, v97
	v_fmac_f32_e32 v2, v6, v97
	v_fmac_f32_e32 v3, v7, v97
	v_mul_f32_e32 v0, v38, v0
	v_mul_f32_e32 v1, v38, v1
	v_mul_f32_e32 v2, v38, v2
	v_mul_f32_e32 v3, v38, v3
	v_mul_f32_e32 v0, 0x3fb8aa3b, v0
	v_mul_f32_e32 v1, 0x3fb8aa3b, v1
	v_mul_f32_e32 v2, 0x3fb8aa3b, v2
	v_mul_f32_e32 v3, 0x3fb8aa3b, v3
	v_exp_f32_e32 v0, v0
	v_exp_f32_e32 v1, v1
	v_exp_f32_e32 v2, v2
	v_exp_f32_e32 v3, v3
	s_nop 0
	v_mul_f32_e32 v88, v88, v0
	v_mul_f32_e32 v89, v89, v1
	v_mul_f32_e32 v90, v90, v2
	v_mul_f32_e32 v91, v91, v3
	ds_write_b128 v39, v[88:91] offset:11264
	global_load_dwordx4 v[204:207], v96, s[8:9]
	global_load_dwordx4 v[208:211], v96, s[8:9] offset:64
	global_load_dwordx4 v[212:215], v96, s[8:9] offset:128
	global_load_dwordx4 v[216:219], v96, s[8:9] offset:192
	s_add_u32 s8, s8, 0x8000
	s_addc_u32 s9, s9, 0
	s_waitcnt vmcnt(12)
	v_mfma_f32_16x16x4_f32 v[88:91], v156, v40, 0
	v_mfma_f32_16x16x4_f32 v[88:91], v157, v41, v[88:91]
	v_mfma_f32_16x16x4_f32 v[88:91], v158, v42, v[88:91]
	v_mfma_f32_16x16x4_f32 v[88:91], v159, v43, v[88:91]
	v_mfma_f32_16x16x4_f32 v[88:91], v160, v44, v[88:91]
	v_mfma_f32_16x16x4_f32 v[88:91], v161, v45, v[88:91]
	v_mfma_f32_16x16x4_f32 v[88:91], v162, v46, v[88:91]
	v_mfma_f32_16x16x4_f32 v[88:91], v163, v47, v[88:91]
	v_mfma_f32_16x16x4_f32 v[88:91], v164, v48, v[88:91]
	v_mfma_f32_16x16x4_f32 v[88:91], v165, v49, v[88:91]
	v_mfma_f32_16x16x4_f32 v[88:91], v166, v50, v[88:91]
	v_mfma_f32_16x16x4_f32 v[88:91], v167, v51, v[88:91]
	v_mfma_f32_16x16x4_f32 v[88:91], v168, v52, v[88:91]
	v_mfma_f32_16x16x4_f32 v[88:91], v169, v53, v[88:91]
	v_mfma_f32_16x16x4_f32 v[88:91], v170, v54, v[88:91]
	v_mfma_f32_16x16x4_f32 v[88:91], v171, v55, v[88:91]
	v_add_u32_e32 v99, 0x600, v98
	v_add_u32_e32 v92, 0, v99
	v_cvt_f32_u32_e32 v92, v92
	v_add_u32_e32 v93, 1, v99
	v_cvt_f32_u32_e32 v93, v93
	v_add_u32_e32 v94, 2, v99
	v_cvt_f32_u32_e32 v94, v94
	v_add_u32_e32 v95, 3, v99
	v_cvt_f32_u32_e32 v95, v95
	v_mul_f32_e32 v0, v97, v92
	v_mul_f32_e32 v1, v97, v93
	v_mul_f32_e32 v2, v97, v94
	v_mul_f32_e32 v3, v97, v95
	v_fma_f32 v4, s11, v0, v92
	v_fma_f32 v5, s11, v1, v93
	v_fma_f32 v6, s11, v2, v94
	v_fma_f32 v7, s11, v3, v95
	v_fmac_f32_e32 v0, v4, v97
	v_fmac_f32_e32 v1, v5, v97
	v_fmac_f32_e32 v2, v6, v97
	v_fmac_f32_e32 v3, v7, v97
	v_mul_f32_e32 v0, v38, v0
	v_mul_f32_e32 v1, v38, v1
	v_mul_f32_e32 v2, v38, v2
	v_mul_f32_e32 v3, v38, v3
	v_mul_f32_e32 v0, 0x3fb8aa3b, v0
	v_mul_f32_e32 v1, 0x3fb8aa3b, v1
	v_mul_f32_e32 v2, 0x3fb8aa3b, v2
	v_mul_f32_e32 v3, 0x3fb8aa3b, v3
	v_exp_f32_e32 v0, v0
	v_exp_f32_e32 v1, v1
	v_exp_f32_e32 v2, v2
	v_exp_f32_e32 v3, v3
	s_nop 0
	v_mul_f32_e32 v88, v88, v0
	v_mul_f32_e32 v89, v89, v1
	v_mul_f32_e32 v90, v90, v2
	v_mul_f32_e32 v91, v91, v3
	ds_write_b128 v39, v[88:91] offset:12288
	s_waitcnt vmcnt(8)
	v_mfma_f32_16x16x4_f32 v[88:91], v172, v40, 0
	v_mfma_f32_16x16x4_f32 v[88:91], v173, v41, v[88:91]
	v_mfma_f32_16x16x4_f32 v[88:91], v174, v42, v[88:91]
	v_mfma_f32_16x16x4_f32 v[88:91], v175, v43, v[88:91]
	v_mfma_f32_16x16x4_f32 v[88:91], v176, v44, v[88:91]
	v_mfma_f32_16x16x4_f32 v[88:91], v177, v45, v[88:91]
	v_mfma_f32_16x16x4_f32 v[88:91], v178, v46, v[88:91]
	v_mfma_f32_16x16x4_f32 v[88:91], v179, v47, v[88:91]
	v_mfma_f32_16x16x4_f32 v[88:91], v180, v48, v[88:91]
	v_mfma_f32_16x16x4_f32 v[88:91], v181, v49, v[88:91]
	v_mfma_f32_16x16x4_f32 v[88:91], v182, v50, v[88:91]
	v_mfma_f32_16x16x4_f32 v[88:91], v183, v51, v[88:91]
	v_mfma_f32_16x16x4_f32 v[88:91], v184, v52, v[88:91]
	v_mfma_f32_16x16x4_f32 v[88:91], v185, v53, v[88:91]
	v_mfma_f32_16x16x4_f32 v[88:91], v186, v54, v[88:91]
	v_mfma_f32_16x16x4_f32 v[88:91], v187, v55, v[88:91]
	v_add_u32_e32 v99, 0x680, v98
	v_add_u32_e32 v92, 0, v99
	v_cvt_f32_u32_e32 v92, v92
	v_add_u32_e32 v93, 1, v99
	v_cvt_f32_u32_e32 v93, v93
	v_add_u32_e32 v94, 2, v99
	v_cvt_f32_u32_e32 v94, v94
	v_add_u32_e32 v95, 3, v99
	v_cvt_f32_u32_e32 v95, v95
	v_mul_f32_e32 v0, v97, v92
	v_mul_f32_e32 v1, v97, v93
	v_mul_f32_e32 v2, v97, v94
	v_mul_f32_e32 v3, v97, v95
	v_fma_f32 v4, s11, v0, v92
	v_fma_f32 v5, s11, v1, v93
	v_fma_f32 v6, s11, v2, v94
	v_fma_f32 v7, s11, v3, v95
	v_fmac_f32_e32 v0, v4, v97
	v_fmac_f32_e32 v1, v5, v97
	v_fmac_f32_e32 v2, v6, v97
	v_fmac_f32_e32 v3, v7, v97
	v_mul_f32_e32 v0, v38, v0
	v_mul_f32_e32 v1, v38, v1
	v_mul_f32_e32 v2, v38, v2
	v_mul_f32_e32 v3, v38, v3
	v_mul_f32_e32 v0, 0x3fb8aa3b, v0
	v_mul_f32_e32 v1, 0x3fb8aa3b, v1
	v_mul_f32_e32 v2, 0x3fb8aa3b, v2
	v_mul_f32_e32 v3, 0x3fb8aa3b, v3
	v_exp_f32_e32 v0, v0
	v_exp_f32_e32 v1, v1
	v_exp_f32_e32 v2, v2
	v_exp_f32_e32 v3, v3
	s_nop 0
	v_mul_f32_e32 v88, v88, v0
	v_mul_f32_e32 v89, v89, v1
	v_mul_f32_e32 v90, v90, v2
	v_mul_f32_e32 v91, v91, v3
	ds_write_b128 v39, v[88:91] offset:13312
	s_waitcnt vmcnt(4)
	v_mfma_f32_16x16x4_f32 v[88:91], v188, v40, 0
	v_mfma_f32_16x16x4_f32 v[88:91], v189, v41, v[88:91]
	v_mfma_f32_16x16x4_f32 v[88:91], v190, v42, v[88:91]
	v_mfma_f32_16x16x4_f32 v[88:91], v191, v43, v[88:91]
	v_mfma_f32_16x16x4_f32 v[88:91], v192, v44, v[88:91]
	v_mfma_f32_16x16x4_f32 v[88:91], v193, v45, v[88:91]
	v_mfma_f32_16x16x4_f32 v[88:91], v194, v46, v[88:91]
	v_mfma_f32_16x16x4_f32 v[88:91], v195, v47, v[88:91]
	v_mfma_f32_16x16x4_f32 v[88:91], v196, v48, v[88:91]
	v_mfma_f32_16x16x4_f32 v[88:91], v197, v49, v[88:91]
	v_mfma_f32_16x16x4_f32 v[88:91], v198, v50, v[88:91]
	v_mfma_f32_16x16x4_f32 v[88:91], v199, v51, v[88:91]
	v_mfma_f32_16x16x4_f32 v[88:91], v200, v52, v[88:91]
	v_mfma_f32_16x16x4_f32 v[88:91], v201, v53, v[88:91]
	v_mfma_f32_16x16x4_f32 v[88:91], v202, v54, v[88:91]
	v_mfma_f32_16x16x4_f32 v[88:91], v203, v55, v[88:91]
	v_add_u32_e32 v99, 0x700, v98
	v_add_u32_e32 v92, 0, v99
	v_cvt_f32_u32_e32 v92, v92
	v_add_u32_e32 v93, 1, v99
	v_cvt_f32_u32_e32 v93, v93
	v_add_u32_e32 v94, 2, v99
	v_cvt_f32_u32_e32 v94, v94
	v_add_u32_e32 v95, 3, v99
	v_cvt_f32_u32_e32 v95, v95
	v_mul_f32_e32 v0, v97, v92
	v_mul_f32_e32 v1, v97, v93
	v_mul_f32_e32 v2, v97, v94
	v_mul_f32_e32 v3, v97, v95
	v_fma_f32 v4, s11, v0, v92
	v_fma_f32 v5, s11, v1, v93
	v_fma_f32 v6, s11, v2, v94
	v_fma_f32 v7, s11, v3, v95
	v_fmac_f32_e32 v0, v4, v97
	v_fmac_f32_e32 v1, v5, v97
	v_fmac_f32_e32 v2, v6, v97
	v_fmac_f32_e32 v3, v7, v97
	v_mul_f32_e32 v0, v38, v0
	v_mul_f32_e32 v1, v38, v1
	v_mul_f32_e32 v2, v38, v2
	v_mul_f32_e32 v3, v38, v3
	v_mul_f32_e32 v0, 0x3fb8aa3b, v0
	v_mul_f32_e32 v1, 0x3fb8aa3b, v1
	v_mul_f32_e32 v2, 0x3fb8aa3b, v2
	v_mul_f32_e32 v3, 0x3fb8aa3b, v3
	v_exp_f32_e32 v0, v0
	v_exp_f32_e32 v1, v1
	v_exp_f32_e32 v2, v2
	v_exp_f32_e32 v3, v3
	s_nop 0
	v_mul_f32_e32 v88, v88, v0
	v_mul_f32_e32 v89, v89, v1
	v_mul_f32_e32 v90, v90, v2
	v_mul_f32_e32 v91, v91, v3
	ds_write_b128 v39, v[88:91] offset:14336
	s_waitcnt vmcnt(0)
	v_mfma_f32_16x16x4_f32 v[88:91], v204, v40, 0
	v_mfma_f32_16x16x4_f32 v[88:91], v205, v41, v[88:91]
	v_mfma_f32_16x16x4_f32 v[88:91], v206, v42, v[88:91]
	v_mfma_f32_16x16x4_f32 v[88:91], v207, v43, v[88:91]
	v_mfma_f32_16x16x4_f32 v[88:91], v208, v44, v[88:91]
	v_mfma_f32_16x16x4_f32 v[88:91], v209, v45, v[88:91]
	v_mfma_f32_16x16x4_f32 v[88:91], v210, v46, v[88:91]
	v_mfma_f32_16x16x4_f32 v[88:91], v211, v47, v[88:91]
	v_mfma_f32_16x16x4_f32 v[88:91], v212, v48, v[88:91]
	v_mfma_f32_16x16x4_f32 v[88:91], v213, v49, v[88:91]
	v_mfma_f32_16x16x4_f32 v[88:91], v214, v50, v[88:91]
	v_mfma_f32_16x16x4_f32 v[88:91], v215, v51, v[88:91]
	v_mfma_f32_16x16x4_f32 v[88:91], v216, v52, v[88:91]
	v_mfma_f32_16x16x4_f32 v[88:91], v217, v53, v[88:91]
	v_mfma_f32_16x16x4_f32 v[88:91], v218, v54, v[88:91]
	v_mfma_f32_16x16x4_f32 v[88:91], v219, v55, v[88:91]
	v_add_u32_e32 v99, 0x780, v98
	v_add_u32_e32 v92, 0, v99
	v_cvt_f32_u32_e32 v92, v92
	v_add_u32_e32 v93, 1, v99
	v_cvt_f32_u32_e32 v93, v93
	v_add_u32_e32 v94, 2, v99
	v_cvt_f32_u32_e32 v94, v94
	v_add_u32_e32 v95, 3, v99
	v_cvt_f32_u32_e32 v95, v95
	v_mul_f32_e32 v0, v97, v92
	v_mul_f32_e32 v1, v97, v93
	v_mul_f32_e32 v2, v97, v94
	v_mul_f32_e32 v3, v97, v95
	v_fma_f32 v4, s11, v0, v92
	v_fma_f32 v5, s11, v1, v93
	v_fma_f32 v6, s11, v2, v94
	v_fma_f32 v7, s11, v3, v95
	v_fmac_f32_e32 v0, v4, v97
	v_fmac_f32_e32 v1, v5, v97
	v_fmac_f32_e32 v2, v6, v97
	v_fmac_f32_e32 v3, v7, v97
	v_mul_f32_e32 v0, v38, v0
	v_mul_f32_e32 v1, v38, v1
	v_mul_f32_e32 v2, v38, v2
	v_mul_f32_e32 v3, v38, v3
	v_mul_f32_e32 v0, 0x3fb8aa3b, v0
	v_mul_f32_e32 v1, 0x3fb8aa3b, v1
	v_mul_f32_e32 v2, 0x3fb8aa3b, v2
	v_mul_f32_e32 v3, 0x3fb8aa3b, v3
	v_exp_f32_e32 v0, v0
	v_exp_f32_e32 v1, v1
	v_exp_f32_e32 v2, v2
	v_exp_f32_e32 v3, v3
	s_nop 0
	v_mul_f32_e32 v88, v88, v0
	v_mul_f32_e32 v89, v89, v1
	v_mul_f32_e32 v90, v90, v2
	v_mul_f32_e32 v91, v91, v3
	ds_write_b128 v39, v[88:91] offset:15360
	s_waitcnt lgkmcnt(0)
	s_barrier
	v_mov_b32_e32 v8, v9
	v_cmp_eq_u32_e32 vcc, 0, v130
	ds_read2st64_b32 v[40:41], v29 offset0:0 offset1:1
	ds_read2st64_b32 v[42:43], v29 offset0:2 offset1:3
	ds_read2st64_b32 v[44:45], v29 offset0:4 offset1:5
	ds_read2st64_b32 v[46:47], v29 offset0:6 offset1:7
	ds_read2st64_b32 v[48:49], v29 offset0:8 offset1:9
	ds_read2st64_b32 v[50:51], v29 offset0:10 offset1:11
	ds_read2st64_b32 v[52:53], v29 offset0:12 offset1:13
	ds_read2st64_b32 v[54:55], v29 offset0:14 offset1:15
	s_waitcnt lgkmcnt(7)
	v_add_f32_e32 v0, v40, v41
	v_add_f32_e64 v1, |v40|, |v41|
	v_cndmask_b32_e64 v1, v1, |v0|, vcc
	v_add_f32_e32 v8, v8, v1
	s_waitcnt lgkmcnt(6)
	v_add_f32_e64 v1, |v42|, |v43|
	v_add_f32_e32 v8, v8, v1
	s_waitcnt lgkmcnt(5)
	v_add_f32_e64 v1, |v44|, |v45|
	v_add_f32_e32 v8, v8, v1
	s_waitcnt lgkmcnt(4)
	v_add_f32_e64 v1, |v46|, |v47|
	v_add_f32_e32 v8, v8, v1
	s_waitcnt lgkmcnt(3)
	v_add_f32_e64 v1, |v48|, |v49|
	v_add_f32_e32 v8, v8, v1
	s_waitcnt lgkmcnt(2)
	v_add_f32_e64 v1, |v50|, |v51|
	v_add_f32_e32 v8, v8, v1
	s_waitcnt lgkmcnt(1)
	v_add_f32_e64 v1, |v52|, |v53|
	v_add_f32_e32 v8, v8, v1
	s_waitcnt lgkmcnt(0)
	v_add_f32_e64 v1, |v54|, |v55|
	v_add_f32_e32 v8, v8, v1
	ds_read2st64_b32 v[40:41], v29 offset0:16 offset1:17
	ds_read2st64_b32 v[42:43], v29 offset0:18 offset1:19
	ds_read2st64_b32 v[44:45], v29 offset0:20 offset1:21
	ds_read2st64_b32 v[46:47], v29 offset0:22 offset1:23
	ds_read2st64_b32 v[48:49], v29 offset0:24 offset1:25
	ds_read2st64_b32 v[50:51], v29 offset0:26 offset1:27
	ds_read2st64_b32 v[52:53], v29 offset0:28 offset1:29
	ds_read2st64_b32 v[54:55], v29 offset0:30 offset1:31
	s_waitcnt lgkmcnt(7)
	v_add_f32_e64 v1, |v40|, |v41|
	v_add_f32_e32 v8, v8, v1
	s_waitcnt lgkmcnt(6)
	v_add_f32_e64 v1, |v42|, |v43|
	v_add_f32_e32 v8, v8, v1
	s_waitcnt lgkmcnt(5)
	v_add_f32_e64 v1, |v44|, |v45|
	v_add_f32_e32 v8, v8, v1
	s_waitcnt lgkmcnt(4)
	v_add_f32_e64 v1, |v46|, |v47|
	v_add_f32_e32 v8, v8, v1
	s_waitcnt lgkmcnt(3)
	v_add_f32_e64 v1, |v48|, |v49|
	v_add_f32_e32 v8, v8, v1
	s_waitcnt lgkmcnt(2)
	v_add_f32_e64 v1, |v50|, |v51|
	v_add_f32_e32 v8, v8, v1
	s_waitcnt lgkmcnt(1)
	v_add_f32_e64 v1, |v52|, |v53|
	v_add_f32_e32 v8, v8, v1
	s_waitcnt lgkmcnt(0)
	v_add_f32_e64 v1, |v54|, |v55|
	v_add_f32_e32 v8, v8, v1
	ds_read2st64_b32 v[40:41], v29 offset0:32 offset1:33
	ds_read2st64_b32 v[42:43], v29 offset0:34 offset1:35
	ds_read2st64_b32 v[44:45], v29 offset0:36 offset1:37
	ds_read2st64_b32 v[46:47], v29 offset0:38 offset1:39
	ds_read2st64_b32 v[48:49], v29 offset0:40 offset1:41
	ds_read2st64_b32 v[50:51], v29 offset0:42 offset1:43
	ds_read2st64_b32 v[52:53], v29 offset0:44 offset1:45
	ds_read2st64_b32 v[54:55], v29 offset0:46 offset1:47
	s_waitcnt lgkmcnt(7)
	v_add_f32_e64 v1, |v40|, |v41|
	v_add_f32_e32 v8, v8, v1
	s_waitcnt lgkmcnt(6)
	v_add_f32_e64 v1, |v42|, |v43|
	v_add_f32_e32 v8, v8, v1
	s_waitcnt lgkmcnt(5)
	v_add_f32_e64 v1, |v44|, |v45|
	v_add_f32_e32 v8, v8, v1
	s_waitcnt lgkmcnt(4)
	v_add_f32_e64 v1, |v46|, |v47|
	v_add_f32_e32 v8, v8, v1
	s_waitcnt lgkmcnt(3)
	v_add_f32_e64 v1, |v48|, |v49|
	v_add_f32_e32 v8, v8, v1
	s_waitcnt lgkmcnt(2)
	v_add_f32_e64 v1, |v50|, |v51|
	v_add_f32_e32 v8, v8, v1
	s_waitcnt lgkmcnt(1)
	v_add_f32_e64 v1, |v52|, |v53|
	v_add_f32_e32 v8, v8, v1
	s_waitcnt lgkmcnt(0)
	v_add_f32_e64 v1, |v54|, |v55|
	v_add_f32_e32 v8, v8, v1
	ds_read2st64_b32 v[40:41], v29 offset0:48 offset1:49
	ds_read2st64_b32 v[42:43], v29 offset0:50 offset1:51
	ds_read2st64_b32 v[44:45], v29 offset0:52 offset1:53
	ds_read2st64_b32 v[46:47], v29 offset0:54 offset1:55
	ds_read2st64_b32 v[48:49], v29 offset0:56 offset1:57
	ds_read2st64_b32 v[50:51], v29 offset0:58 offset1:59
	ds_read2st64_b32 v[52:53], v29 offset0:60 offset1:61
	ds_read2st64_b32 v[54:55], v29 offset0:62 offset1:63
	s_waitcnt lgkmcnt(7)
	v_add_f32_e64 v1, |v40|, |v41|
	v_add_f32_e32 v8, v8, v1
	s_waitcnt lgkmcnt(6)
	v_add_f32_e64 v1, |v42|, |v43|
	v_add_f32_e32 v8, v8, v1
	s_waitcnt lgkmcnt(5)
	v_add_f32_e64 v1, |v44|, |v45|
	v_add_f32_e32 v8, v8, v1
	s_waitcnt lgkmcnt(4)
	v_add_f32_e64 v1, |v46|, |v47|
	v_add_f32_e32 v8, v8, v1
	s_waitcnt lgkmcnt(3)
	v_add_f32_e64 v1, |v48|, |v49|
	v_add_f32_e32 v8, v8, v1
	s_waitcnt lgkmcnt(2)
	v_add_f32_e64 v1, |v50|, |v51|
	v_add_f32_e32 v8, v8, v1
	s_waitcnt lgkmcnt(1)
	v_add_f32_e64 v1, |v52|, |v53|
	v_add_f32_e32 v8, v8, v1
	s_waitcnt lgkmcnt(0)
	v_add_f32_e64 v1, |v54|, |v55|
	v_add_f32_e32 v8, v8, v1
